# LRU tile loop, fewer VALU: 1-av^2 by v_fma clamp, local scan second half as plain fmac/mul chains, rescan with 16 LDS reads up front and paired cvt_pk + store_short/_d16_hi
# speedup vs baseline: 1.0209x; 1.0007x over previous
.LBB0_932:
	s_waitcnt lgkmcnt(0)
	ds_read_b128 v[98:101], v170
	ds_read_b128 v[102:105], v170 offset:16
	ds_read_b128 v[166:169], v170 offset:128
	ds_read_b128 v[178:181], v170 offset:144
	ds_read2_b32 v[182:183], v109 offset1:16
	s_waitcnt lgkmcnt(4)
	v_cvt_pk_bf16_f32 v162, v98, v99
	v_cvt_pk_bf16_f32 v163, v100, v101
	s_waitcnt lgkmcnt(3)
	v_cvt_pk_bf16_f32 v164, v102, v103
	v_cvt_pk_bf16_f32 v165, v104, v105
	s_waitcnt lgkmcnt(2)
	v_cvt_pk_bf16_f32 v166, v166, v167
	v_cvt_pk_bf16_f32 v167, v168, v169
	s_waitcnt lgkmcnt(1)
	v_cvt_pk_bf16_f32 v168, v178, v179
	v_cvt_pk_bf16_f32 v169, v180, v181
	v_mfma_f32_16x16x32_bf16 v[98:101], v[162:165], v[6:9], v[66:69]
	s_nop 0
	v_mfma_f32_16x16x32_bf16 v[178:181], v[166:169], v[2:5], v[98:101]
	v_mfma_f32_16x16x32_bf16 v[190:193], v[162:165], v[34:37], v[82:85]
	v_mfma_f32_16x16x32_bf16 v[190:193], v[166:169], v[38:41], v[190:193]
	s_nop 5
	v_mul_f32_e32 v98, 0xbfb8aa3b, v178
	v_exp_f32_e32 v98, v98
	v_mfma_f32_16x16x32_bf16 v[102:105], v[162:165], v[10:13], v[70:73]
	v_add_f32_e32 v98, 1.0, v98
	v_rcp_f32_e32 v98, v98
	v_mul_f32_e32 v99, 0xbfb8aa3b, v190
	v_exp_f32_e32 v99, v99
	v_mfma_f32_16x16x32_bf16 v[194:197], v[166:169], v[14:17], v[102:105]
	v_mul_f32_e32 v98, v121, v98
	v_exp_f32_e32 v145, v98
	v_add_f32_e32 v98, 1.0, v99
	v_mul_f32_e32 v102, 0xbfb8aa3b, v179
	v_rcp_f32_e32 v103, v98
	v_fma_f32 v104, -v145, v145, 1.0 clamp
	s_nop 0
	v_exp_f32_e32 v178, v102
	v_sqrt_f32_e32 v104, v104
	s_waitcnt lgkmcnt(0)
	v_mul_f32_e32 v102, v103, v182
	v_mul_f32_e32 v182, 0xbfb8aa3b, v191
	v_add_f32_e32 v178, 1.0, v178
	v_mul_f32_e32 v179, v104, v102
	v_mfma_f32_16x16x32_bf16 v[102:105], v[162:165], v[42:45], v[86:89]
	v_rcp_f32_e32 v178, v178
	v_exp_f32_e32 v182, v182
	v_mul_f32_e32 v190, 0xbfb8aa3b, v195
	v_mfma_f32_16x16x32_bf16 v[198:201], v[166:169], v[46:49], v[102:105]
	v_exp_f32_e32 v190, v190
	v_add_f32_e32 v182, 1.0, v182
	v_rcp_f32_e32 v182, v182
	s_nop 0
	v_mul_f32_e32 v102, v121, v178
	v_exp_f32_e32 v178, v102
	v_mfma_f32_16x16x32_bf16 v[102:105], v[162:165], v[50:53], v[94:97]
	v_fma_f32 v185, -v178, v178, 1.0 clamp
	v_mfma_f32_16x16x32_bf16 v[202:205], v[166:169], v[54:57], v[102:105]
	s_nop 0
	s_nop 4
	v_mul_f32_e32 v102, 0xbfb8aa3b, v180
	v_mfma_f32_16x16x32_bf16 v[186:189], v[162:165], v[18:21], v[74:77]
	v_exp_f32_e32 v180, v102
	v_mfma_f32_16x16x32_bf16 v[98:101], v[162:165], v[26:29], v[78:81]
	v_mfma_f32_16x16x32_bf16 v[102:105], v[162:165], v[58:61], v[90:93]
	ds_read2_b32 v[162:163], v109 offset0:64 offset1:80
	v_sqrt_f32_e32 v164, v185
	v_add_f32_e32 v165, 1.0, v180
	v_mfma_f32_16x16x32_bf16 v[186:189], v[166:169], v[22:25], v[186:189]
	v_rcp_f32_e32 v165, v165
	s_waitcnt lgkmcnt(0)
	v_mul_f32_e32 v162, v182, v162
	v_mul_f32_e32 v162, v164, v162
	v_mfma_f32_16x16x32_bf16 v[98:101], v[166:169], v[30:33], v[98:101]
	v_mul_f32_e32 v165, v121, v165
	v_mul_f32_e32 v182, 0xbfb8aa3b, v194
	v_exp_f32_e32 v182, v182
	v_mfma_f32_16x16x32_bf16 v[102:105], v[166:169], v[62:65], v[102:105]
	v_mul_f32_e32 v166, 0xbfb8aa3b, v192
	v_exp_f32_e32 v166, v166
	v_exp_f32_e32 v168, v165
	s_nop 0
	v_mul_f32_e32 v98, 0xbfb8aa3b, v98
	v_exp_f32_e32 v98, v98
	v_add_f32_e32 v164, 1.0, v166
	v_rcp_f32_e32 v166, v164
	v_mul_f32_e32 v164, 0xbfb8aa3b, v181
	v_exp_f32_e32 v169, v164
	ds_read2_b32 v[164:165], v109 offset0:128 offset1:144
	v_fma_f32 v167, -v168, v168, 1.0 clamp
	s_nop 0
	v_sqrt_f32_e32 v167, v167
	v_add_f32_e32 v169, 1.0, v169
	s_waitcnt lgkmcnt(0)
	v_mul_f32_e32 v164, v166, v164
	v_mul_f32_e32 v166, 0xbfb8aa3b, v193
	v_exp_f32_e32 v166, v166
	v_rcp_f32_e32 v169, v169
	v_mul_f32_e32 v164, v167, v164
	v_add_f32_e32 v98, 1.0, v98
	v_add_f32_e32 v166, 1.0, v166
	v_rcp_f32_e32 v180, v166
	ds_read2_b32 v[166:167], v109 offset0:192 offset1:208
	v_mul_f32_e32 v169, v121, v169
	v_exp_f32_e32 v169, v169
	v_rcp_f32_e32 v98, v98
	v_mul_f32_e32 v102, 0xbfb8aa3b, v102
	s_waitcnt lgkmcnt(0)
	v_mul_f32_e32 v166, v180, v166
	v_add_f32_e32 v180, 1.0, v182
	v_fma_f32 v181, -v169, v169, 1.0 clamp
	v_rcp_f32_e32 v180, v180
	v_mul_f32_e32 v182, 0xbfb8aa3b, v198
	v_sqrt_f32_e32 v181, v181
	v_exp_f32_e32 v182, v182
	v_mul_f32_e32 v180, v120, v180
	v_exp_f32_e32 v180, v180
	v_mul_f32_e32 v166, v181, v166
	v_add_f32_e32 v181, 1.0, v182
	v_rcp_f32_e32 v181, v181
	v_fma_f32 v185, -v180, v180, 1.0 clamp
	v_add_u32_e32 v182, 0x1000, v109
	v_sqrt_f32_e32 v185, v185
	ds_write2_b32 v182, v145, v180 offset1:16
	v_mul_f32_e32 v145, v181, v183
	v_mul_f32_e32 v183, 0xbfb8aa3b, v199
	v_exp_f32_e32 v183, v183
	v_add_f32_e32 v180, 1.0, v190
	v_mul_f32_e32 v145, v185, v145
	v_rcp_f32_e32 v180, v180
	v_add_u32_e32 v181, 0x2000, v109
	ds_write2_b32 v181, v179, v145 offset1:16
	v_add_f32_e32 v145, 1.0, v183
	v_mul_f32_e32 v179, 0xbfb8aa3b, v196
	v_rcp_f32_e32 v145, v145
	v_exp_f32_e32 v179, v179
	v_mul_f32_e32 v180, v120, v180
	v_exp_f32_e32 v180, v180
	v_mul_f32_e32 v145, v145, v163
	v_add_f32_e32 v163, 1.0, v179
	v_rcp_f32_e32 v163, v163
	ds_write2_b32 v182, v178, v180 offset0:64 offset1:80
	v_fma_f32 v178, -v180, v180, 1.0 clamp
	v_sqrt_f32_e32 v178, v178
	v_mul_f32_e32 v163, v120, v163
	v_exp_f32_e32 v163, v163
	v_mul_f32_e32 v98, v122, v98
	v_mul_f32_e32 v145, v178, v145
	v_mul_f32_e32 v178, 0xbfb8aa3b, v200
	v_exp_f32_e32 v178, v178
	ds_write2_b32 v181, v162, v145 offset0:64 offset1:80
	ds_write2_b32 v182, v168, v163 offset0:128 offset1:144
	v_fma_f32 v162, -v163, v163, 1.0 clamp
	v_mul_f32_e32 v163, 0xbfb8aa3b, v197
	v_exp_f32_e32 v163, v163
	v_add_f32_e32 v145, 1.0, v178
	v_rcp_f32_e32 v145, v145
	v_add_f32_e32 v163, 1.0, v163
	v_sqrt_f32_e32 v162, v162
	v_rcp_f32_e32 v163, v163
	v_mul_f32_e32 v145, v145, v165
	v_exp_f32_e32 v102, v102
	v_mul_f32_e32 v145, v162, v145
	v_mul_f32_e32 v162, 0xbfb8aa3b, v201
	v_mul_f32_e32 v163, v120, v163
	v_exp_f32_e32 v162, v162
	v_exp_f32_e32 v163, v163
	ds_write2_b32 v181, v164, v145 offset0:128 offset1:144
	v_exp_f32_e32 v98, v98
	v_add_f32_e32 v145, 1.0, v162
	ds_write2_b32 v182, v169, v163 offset0:192 offset1:208
	v_fma_f32 v162, -v163, v163, 1.0 clamp
	v_mul_f32_e32 v163, 0xbfb8aa3b, v186
	v_rcp_f32_e32 v145, v145
	v_exp_f32_e32 v163, v163
	v_sqrt_f32_e32 v162, v162
	v_mul_f32_e32 v145, v145, v167
	v_add_f32_e32 v163, 1.0, v163
	v_rcp_f32_e32 v163, v163
	v_mul_f32_e32 v145, v162, v145
	v_mul_f32_e32 v162, 0xbfb8aa3b, v202
	v_exp_f32_e32 v162, v162
	v_mul_f32_e32 v163, v123, v163
	v_exp_f32_e32 v178, v163
	ds_write2_b32 v181, v166, v145 offset0:192 offset1:208
	v_add_f32_e32 v145, 1.0, v162
	v_mul_f32_e32 v162, 0xbfb8aa3b, v187
	v_mul_f32_e32 v99, 0xbfb8aa3b, v99
	v_exp_f32_e32 v165, v162
	v_exp_f32_e32 v99, v99
	ds_read2_b32 v[162:163], v109 offset0:32 offset1:48
	v_add_f32_e32 v102, 1.0, v102
	ds_write2_b32 v182, v178, v98 offset0:32 offset1:48
	v_fma_f32 v98, -v98, v98, 1.0 clamp
	v_add_f32_e32 v165, 1.0, v165
	v_rcp_f32_e32 v102, v102
	v_add_f32_e32 v99, 1.0, v99
	v_rcp_f32_e32 v165, v165
	v_sqrt_f32_e32 v98, v98
	v_rcp_f32_e32 v99, v99
	v_fma_f32 v164, -v178, v178, 1.0 clamp
	v_rcp_f32_e32 v145, v145
	s_waitcnt lgkmcnt(1)
	v_mul_f32_e32 v102, v102, v163
	v_sqrt_f32_e32 v164, v164
	v_mul_f32_e32 v165, v123, v165
	v_mul_f32_e32 v98, v98, v102
	v_mul_f32_e32 v102, 0xbfb8aa3b, v103
	v_mul_f32_e32 v99, v122, v99
	v_exp_f32_e32 v179, v165
	v_exp_f32_e32 v102, v102
	v_exp_f32_e32 v99, v99
	v_mul_f32_e32 v145, v145, v162
	v_mul_f32_e32 v162, 0xbfb8aa3b, v203
	v_mul_f32_e32 v145, v164, v145
	v_mul_f32_e32 v164, 0xbfb8aa3b, v188
	v_exp_f32_e32 v162, v162
	v_exp_f32_e32 v167, v164
	ds_read2_b32 v[164:165], v109 offset0:96 offset1:112
	ds_write2_b32 v181, v145, v98 offset0:32 offset1:48
	v_add_f32_e32 v98, 1.0, v102
	ds_write2_b32 v182, v179, v99 offset0:96 offset1:112
	v_fma_f32 v99, -v99, v99, 1.0 clamp
	v_rcp_f32_e32 v98, v98
	v_sqrt_f32_e32 v99, v99
	v_add_f32_e32 v162, 1.0, v162
	v_fma_f32 v166, -v179, v179, 1.0 clamp
	v_rcp_f32_e32 v162, v162
	v_mul_f32_e32 v100, 0xbfb8aa3b, v100
	s_waitcnt lgkmcnt(2)
	v_mul_f32_e32 v98, v98, v165
	v_sqrt_f32_e32 v166, v166
	v_exp_f32_e32 v100, v100
	v_mul_f32_e32 v98, v99, v98
	v_mul_f32_e32 v99, 0xbfb8aa3b, v104
	v_exp_f32_e32 v99, v99
	v_mul_f32_e32 v162, v162, v164
	v_add_f32_e32 v167, 1.0, v167
	v_mul_f32_e32 v162, v166, v162
	v_add_f32_e32 v100, 1.0, v100
	v_rcp_f32_e32 v167, v167
	v_mul_f32_e32 v164, 0xbfb8aa3b, v204
	v_mul_f32_e32 v166, 0xbfb8aa3b, v189
	v_rcp_f32_e32 v100, v100
	ds_write2_b32 v181, v162, v98 offset0:96 offset1:112
	v_add_f32_e32 v98, 1.0, v99
	v_mul_f32_e32 v99, 0xbfb8aa3b, v101
	v_exp_f32_e32 v164, v164
	v_exp_f32_e32 v169, v166
	v_exp_f32_e32 v99, v99
	v_mul_f32_e32 v167, v123, v167
	v_mul_f32_e32 v100, v122, v100
	v_exp_f32_e32 v180, v167
	v_add_f32_e32 v164, 1.0, v164
	ds_read2_b32 v[166:167], v109 offset0:160 offset1:176
	v_add_f32_e32 v169, 1.0, v169
	v_exp_f32_e32 v100, v100
	v_add_f32_e32 v99, 1.0, v99
	v_rcp_f32_e32 v164, v164
	v_rcp_f32_e32 v169, v169
	v_rcp_f32_e32 v99, v99
	v_fma_f32 v168, -v180, v180, 1.0 clamp
	ds_write2_b32 v182, v180, v100 offset0:160 offset1:176
	v_fma_f32 v100, -v100, v100, 1.0 clamp
	s_waitcnt lgkmcnt(1)
	v_mul_f32_e32 v164, v164, v166
	v_mul_f32_e32 v166, 0xbfb8aa3b, v205
	v_mul_f32_e32 v169, v123, v169
	v_rcp_f32_e32 v98, v98
	v_mul_f32_e32 v101, 0xbfb8aa3b, v105
	v_mul_f32_e32 v99, v122, v99
	v_sqrt_f32_e32 v168, v168
	v_exp_f32_e32 v166, v166
	v_exp_f32_e32 v183, v169
	v_sqrt_f32_e32 v100, v100
	v_exp_f32_e32 v101, v101
	v_exp_f32_e32 v99, v99
	v_mul_f32_e32 v98, v98, v167
	v_mul_f32_e32 v164, v168, v164
	v_add_f32_e32 v166, 1.0, v166
	v_fma_f32 v185, -v183, v183, 1.0 clamp
	ds_read2_b32 v[168:169], v109 offset0:224 offset1:240
	v_mul_f32_e32 v98, v100, v98
	v_add_f32_e32 v100, 1.0, v101
	v_fma_f32 v101, -v99, v99, 1.0 clamp
	v_rcp_f32_e32 v166, v166
	v_rcp_f32_e32 v100, v100
	v_sqrt_f32_e32 v185, v185
	v_sqrt_f32_e32 v101, v101
	s_waitcnt lgkmcnt(0)
	v_mul_f32_e32 v166, v166, v168
	ds_write2_b32 v181, v164, v98 offset0:160 offset1:176
	ds_write2_b32 v182, v183, v99 offset0:224 offset1:240
	v_mul_f32_e32 v98, v100, v169
	v_mul_f32_e32 v166, v185, v166
	v_mul_f32_e32 v98, v101, v98
	ds_write2_b32 v181, v166, v98 offset0:224 offset1:240
	s_waitcnt lgkmcnt(0)
	ds_read2st64_b32 v[98:99], v1 offset0:32 offset1:33
	ds_read2st64_b32 v[100:101], v1 offset0:16 offset1:17
	ds_read2st64_b32 v[102:103], v1 offset0:18 offset1:19
	ds_read2st64_b32 v[104:105], v1 offset0:20 offset1:21
	ds_read2st64_b32 v[162:163], v1 offset0:22 offset1:23
	ds_read2st64_b32 v[164:165], v1 offset0:34 offset1:35
	ds_read2st64_b32 v[166:167], v1 offset0:36 offset1:37
	ds_read2st64_b32 v[168:169], v1 offset0:38 offset1:39
	s_waitcnt lgkmcnt(6)
	v_fma_f32 v98, 0, v100, v98
	v_fmac_f32_e32 v99, v98, v101
	s_waitcnt lgkmcnt(2)
	v_fma_f32 v98, v99, v102, v164
	v_fmac_f32_e32 v165, v98, v103
	s_waitcnt lgkmcnt(1)
	v_fma_f32 v98, v165, v104, v166
	v_fmac_f32_e32 v167, v98, v105
	s_waitcnt lgkmcnt(0)
	v_fma_f32 v98, v167, v162, v168
	v_fmac_f32_e32 v169, v98, v163
	ds_read2st64_b32 v[98:99], v1 offset0:40 offset1:41
	ds_read2st64_b32 v[164:165], v1 offset0:24 offset1:25
	ds_read2st64_b32 v[166:167], v1 offset0:26 offset1:27
	ds_read2st64_b32 v[178:179], v1 offset0:28 offset1:29
	ds_read2st64_b32 v[180:181], v1 offset0:30 offset1:31
	ds_read2st64_b32 v[182:183], v1 offset0:42 offset1:43
	ds_read2st64_b32 v[186:187], v1 offset0:44 offset1:45
	ds_read2st64_b32 v[188:189], v1 offset0:46 offset1:47
	v_mul_f32_e32 v101, v100, v101
	v_mul_f32_e32 v101, v101, v102
	v_mul_f32_e32 v101, v101, v103
	v_mul_f32_e32 v101, v101, v104
	v_mul_f32_e32 v101, v101, v105
	v_mul_f32_e32 v101, v101, v162
	v_mul_f32_e32 v101, v101, v163
	s_waitcnt lgkmcnt(6)
	v_fmac_f32_e32 v98, v169, v164
	v_mul_f32_e32 v101, v101, v164
	v_fmac_f32_e32 v99, v98, v165
	v_mul_f32_e32 v101, v101, v165
	s_waitcnt lgkmcnt(2)
	v_fmac_f32_e32 v182, v99, v166
	v_mul_f32_e32 v101, v101, v166
	v_fmac_f32_e32 v183, v182, v167
	v_mul_f32_e32 v101, v101, v167
	s_waitcnt lgkmcnt(1)
	v_fmac_f32_e32 v186, v183, v178
	v_mul_f32_e32 v101, v101, v178
	v_fmac_f32_e32 v187, v186, v179
	v_mul_f32_e32 v101, v101, v179
	s_waitcnt lgkmcnt(0)
	v_fmac_f32_e32 v188, v187, v180
	v_mul_f32_e32 v101, v101, v180
	v_fmac_f32_e32 v189, v188, v181
	v_mul_f32_e32 v101, v101, v181
	v_mov_b32_e32 v98, v189
	s_branch .LBB0_934

.Lp6_zwait_done:
	s_andn2_b64 vcc, exec, s[28:29]
	s_waitcnt lgkmcnt(7)
	v_fmac_f32_e32 v165, v177, v164
	s_cbranch_vccnz .LBB0_937
	v_cndmask_b32_e64 v145, v165, v177, s[4:5]
	s_waitcnt lgkmcnt(6)
	v_fma_f32 v164, v168, v145, v169
	v_cndmask_b32_e64 v145, v145, v164, s[18:19]
	s_waitcnt lgkmcnt(5)
	v_fma_f32 v164, v166, v145, v167
	v_cndmask_b32_e64 v145, v145, v164, s[16:17]
	s_waitcnt lgkmcnt(4)
	v_fma_f32 v164, v162, v145, v163
	v_cndmask_b32_e64 v145, v145, v164, s[14:15]
	s_waitcnt lgkmcnt(3)
	v_fma_f32 v164, v104, v145, v105
	v_cndmask_b32_e64 v145, v145, v164, s[12:13]
	s_waitcnt lgkmcnt(2)
	v_fma_f32 v164, v102, v145, v103
	v_cndmask_b32_e64 v145, v145, v164, s[10:11]
	s_waitcnt lgkmcnt(1)
	v_fma_f32 v164, v100, v145, v101
	v_cndmask_b32_e64 v145, v145, v164, s[8:9]
	s_waitcnt lgkmcnt(0)
	v_fma_f32 v164, v98, v145, v99
	v_cndmask_b32_e64 v145, v145, v164, s[6:7]
	ds_read2st64_b32 v[178:179], v1 offset0:32 offset1:33
	ds_read2st64_b32 v[180:181], v1 offset0:16 offset1:17
	ds_read2st64_b32 v[182:183], v1 offset0:18 offset1:19
	ds_read2st64_b32 v[186:187], v1 offset0:20 offset1:21
	ds_read2st64_b32 v[188:189], v1 offset0:22 offset1:23
	ds_read2st64_b32 v[190:191], v1 offset0:34 offset1:35
	ds_read2st64_b32 v[192:193], v1 offset0:36 offset1:37
	ds_read2st64_b32 v[194:195], v1 offset0:38 offset1:39
	ds_read2st64_b32 v[206:207], v1 offset0:40 offset1:41
	ds_read2st64_b32 v[208:209], v1 offset0:24 offset1:25
	ds_read2st64_b32 v[210:211], v1 offset0:26 offset1:27
	ds_read2st64_b32 v[212:213], v1 offset0:28 offset1:29
	ds_read2st64_b32 v[214:215], v1 offset0:30 offset1:31
	ds_read2st64_b32 v[216:217], v1 offset0:42 offset1:43
	ds_read2st64_b32 v[218:219], v1 offset0:44 offset1:45
	ds_read2st64_b32 v[220:221], v1 offset0:46 offset1:47
	v_add_co_u32_e32 v196, vcc, s77, v158
	s_nop 1
	v_addc_co_u32_e32 v197, vcc, -1, v159, vcc
	s_waitcnt lgkmcnt(14)
	v_fma_f32 v145, v145, v180, v178
	v_fmac_f32_e32 v179, v145, v181
	v_mul_f32_e32 v222, v125, v145
	v_mul_f32_e32 v223, v124, v179
	v_cvt_pk_bf16_f32 v222, v222, v223
	global_store_short v[196:197], v222, off offset:-1920
	global_store_short_d16_hi v[196:197], v222, off offset:-1792
	s_waitcnt lgkmcnt(10)
	v_fma_f32 v145, v179, v182, v190
	v_fmac_f32_e32 v191, v145, v183
	v_mul_f32_e32 v224, v127, v145
	v_mul_f32_e32 v225, v126, v191
	v_cvt_pk_bf16_f32 v224, v224, v225
	global_store_short v[196:197], v224, off offset:-1664
	global_store_short_d16_hi v[196:197], v224, off offset:-1536
	s_waitcnt lgkmcnt(9)
	v_fma_f32 v145, v191, v186, v192
	v_fmac_f32_e32 v193, v145, v187
	v_mul_f32_e32 v222, v131, v145
	v_mul_f32_e32 v223, v130, v193
	v_cvt_pk_bf16_f32 v222, v222, v223
	global_store_short v[196:197], v222, off offset:-1408
	global_store_short_d16_hi v[196:197], v222, off offset:-1280
	s_waitcnt lgkmcnt(8)
	v_fma_f32 v145, v193, v188, v194
	v_fmac_f32_e32 v195, v145, v189
	v_mul_f32_e32 v224, v135, v145
	v_mul_f32_e32 v225, v134, v195
	v_cvt_pk_bf16_f32 v224, v224, v225
	global_store_short v[196:197], v224, off offset:-1152
	global_store_short_d16_hi v[196:197], v224, off offset:-1024
	s_waitcnt lgkmcnt(6)
	v_fma_f32 v145, v195, v208, v206
	v_fmac_f32_e32 v207, v145, v209
	v_mul_f32_e32 v222, v139, v145
	v_mul_f32_e32 v223, v138, v207
	v_cvt_pk_bf16_f32 v222, v222, v223
	global_store_short v[196:197], v222, off offset:-896
	global_store_short_d16_hi v[196:197], v222, off offset:-768
	s_waitcnt lgkmcnt(2)
	v_fma_f32 v145, v207, v210, v216
	v_fmac_f32_e32 v217, v145, v211
	v_mul_f32_e32 v224, v143, v145
	v_mul_f32_e32 v225, v142, v217
	v_cvt_pk_bf16_f32 v224, v224, v225
	global_store_short v[196:197], v224, off offset:-640
	global_store_short_d16_hi v[196:197], v224, off offset:-512
	s_waitcnt lgkmcnt(1)
	v_fma_f32 v145, v217, v212, v218
	v_fmac_f32_e32 v219, v145, v213
	v_mul_f32_e32 v222, v149, v145
	v_mul_f32_e32 v223, v148, v219
	v_cvt_pk_bf16_f32 v222, v222, v223
	global_store_short v[196:197], v222, off offset:-384
	global_store_short_d16_hi v[196:197], v222, off offset:-256
	s_waitcnt lgkmcnt(0)
	v_fma_f32 v145, v219, v214, v220
	v_fmac_f32_e32 v221, v145, v215
	v_mul_f32_e32 v224, v153, v145
	v_mul_f32_e32 v225, v152, v221
	v_cvt_pk_bf16_f32 v224, v224, v225
	global_store_short v[196:197], v224, off offset:-128
	global_store_short_d16_hi v[196:197], v224, off
	s_andn2_b64 vcc, exec, s[26:27]
	s_cbranch_vccnz .LBB0_937
	global_load_short_d16_hi v135, v[158:159], off offset:-1152 nt
	global_load_short_d16_hi v131, v[158:159], off offset:-1408 nt
	global_load_short_d16_hi v127, v[158:159], off offset:-1664 nt
	global_load_short_d16_hi v125, v[158:159], off offset:-1920 nt
	global_load_short_d16_hi v124, v[158:159], off offset:-1792 nt
	global_load_short_d16_hi v126, v[158:159], off offset:-1536 nt
	global_load_short_d16_hi v130, v[158:159], off offset:-1280 nt
	global_load_short_d16_hi v134, v[158:159], off offset:-1024 nt
	global_load_short_d16_hi v153, v[158:159], off offset:-128 nt
	global_load_short_d16_hi v149, v[158:159], off offset:-384 nt
	global_load_short_d16_hi v143, v[158:159], off offset:-640 nt
	global_load_short_d16_hi v139, v[158:159], off offset:-896 nt
	global_load_short_d16_hi v138, v[158:159], off offset:-768 nt
	global_load_short_d16_hi v142, v[158:159], off offset:-512 nt
	global_load_short_d16_hi v148, v[158:159], off offset:-256 nt
	global_load_short_d16_hi v152, v[158:159], off nt
